# layout 5 (conv-mixer projection weight transposes W9/W10 deferred too) + nt streaming stores
# speedup vs baseline: 1.0036x; 1.0019x over previous
.LBB0_35:
	s_or_b64 exec, exec, s[4:5]
	s_lshl_b32 s4, s14, 14
	s_add_i32 s4, s4, 0
	s_add_u32 s19, s16, 0x76b32000
	s_addc_u32 s23, s17, 0
	s_add_u32 s25, s16, 0x6eb32000
	s_addc_u32 s40, s17, 0
	s_add_u32 s41, s16, 0x6ab32000
	s_addc_u32 s42, s17, 0
	s_add_u32 s43, s16, 0x6bb32000
	s_addc_u32 s44, s17, 0
	s_add_u32 s13, s16, 0x69332000
	s_addc_u32 s15, s17, 0
	s_add_u32 s45, s16, 0x68732000
	s_addc_u32 s47, s17, 0
	s_add_u32 s48, s16, 0x68132000
	s_addc_u32 s49, s17, 0
	s_add_u32 s50, s16, 0x67732000
	s_addc_u32 s51, s17, 0
	v_lshrrev_b32_e32 v40, 3, v1
	s_add_u32 s52, s16, 0x69b32000
	v_mul_u32_u24_e32 v5, 0x420, v10
	v_lshlrev_b32_e32 v6, 2, v40
	s_addc_u32 s53, s17, 0
	v_lshl_add_u32 v3, v10, 4, s4
	v_add3_u32 v51, s4, v5, v6
	s_lshl_b32 s54, s46, 10
	s_lshl_b32 s4, s14, 7
	s_add_i32 s54, s54, s4
	s_lshl_b32 s4, s14, 6
	v_lshlrev_b32_e32 v34, 2, v1
	s_add_i32 s56, s56, s4
	s_lshl_b32 s4, s46, 8
	s_lshl_b32 s5, s14, 5
	v_and_b32_e32 v2, 28, v34
	v_mov_b32_e32 v43, 0
	v_mul_u32_u24_e32 v4, 0x84, v40
	v_or_b32_e32 v35, 8, v40
	v_or_b32_e32 v49, 16, v40
	v_or_b32_e32 v50, 24, v40
	v_lshlrev_b32_e32 v52, 1, v40
	v_mov_b32_e32 v5, 0x800
	s_add_i32 s57, s4, s5
	s_mov_b32 s7, 0
	v_or_b32_e32 v53, 0x800, v52
	v_lshl_or_b32 v54, v35, 1, v5
	v_lshl_or_b32 v55, v49, 1, v5
	v_lshl_or_b32 v56, v50, 1, v5
	v_mov_b32_e32 v41, v43
	s_lshl_b32 s55, s58, 10
	s_addk_i32 s57, 0xfe00
	s_lshl_b32 s58, s58, 8
	v_lshlrev_b32_e32 v42, 2, v2
	s_movk_i32 s59, 0x1000
	s_movk_i32 s60, 0x7ff
	s_mov_b32 s61, 0x2aaaaaab
	s_movk_i32 s62, 0xc0
	s_movk_i32 s63, 0x7f
	s_movk_i32 s64, 0xff40
	s_movk_i32 s65, 0x1ff
	v_add_u32_e32 v57, v3, v4
	s_mov_b32 s66, 12
	s_branch .LBB0_37

.Ldj0_all:
	v_readfirstlane_b32 s5, v0
	s_lshr_b32 s5, s5, 6
	s_lshl_b32 s2, s2, 3
	s_add_u32 s2, s2, s5
	s_lshl_b32 s92, s4, 3
	v_mbcnt_lo_u32_b32 v41, -1, 0
	v_mbcnt_hi_u32_b32 v41, -1, v41
	v_lshrrev_b32_e32 v42, 3, v41
	v_and_b32_e32 v43, 7, v41
	v_lshlrev_b32_e32 v44, 13, v42
	v_lshl_add_u32 v44, v43, 4, v44
	v_add_u32_e32 v45, 0x10000, v44
	v_add_u32_e32 v46, 0x20000, v44
	v_add_u32_e32 v47, 0x30000, v44
	v_add_u32_e32 v48, 0x40000, v44
	v_add_u32_e32 v49, 0x50000, v44
	v_add_u32_e32 v50, 0x60000, v44
	v_add_u32_e32 v51, 0x70000, v44
	s_lshl_b32 s49, s5, 14
	v_mul_u32_u24_e32 v52, 0x84, v42
	v_lshl_add_u32 v52, v43, 4, v52
	v_add_u32_e32 v52, s49, v52
	v_mul_u32_u24_e32 v53, 0x420, v43
	v_lshl_add_u32 v53, v42, 2, v53
	v_add_u32_e32 v53, s49, v53
	v_lshlrev_b32_e32 v54, 12, v42
	v_lshl_add_u32 v54, v43, 4, v54
	v_add_u32_e32 v55, 0x8000, v54
	v_add_u32_e32 v56, 0x10000, v54
	v_add_u32_e32 v57, 0x18000, v54
	s_mov_b32 s83, 0
.Ldj0_disp:
	s_cmp_eq_u32 s83, 0
	s_cbranch_scc0 .Ldj0_nx0
	s_add_u32 s83, s83, 1
	s_cmp_eq_u32 s3, 0
	s_cbranch_scc0 .Ldj0_disp
	s_mov_b32 s69, 0
	s_mov_b32 s91, 0x0
	s_mov_b32 s93, 0x800
	s_branch .Ldj0_job
.Ldj0_nx0:
	s_cmp_eq_u32 s83, 1
	s_cbranch_scc0 .Ldj0_nx1
	s_add_u32 s83, s83, 1
	s_cmp_eq_u32 s3, 2
	s_cbranch_scc0 .Ldj0_disp
	s_mov_b32 s69, 1
	s_mov_b32 s91, 0x0
	s_mov_b32 s93, 0x800
	s_branch .Ldj0_job

.Ldj0_job:
	s_add_u32 s91, s91, s2
	s_cmp_ge_u32 s91, s93
	s_cbranch_scc1 .Ldj0_disp
	s_load_dwordx2 s[6:7], s[86:87], 0x80
	s_load_dwordx2 s[88:89], s[86:87], 0xb0
	s_mul_i32 s48, s69, 0x1000000
	s_waitcnt lgkmcnt(0)
	s_add_u32 s6, s6, s48
	s_addc_u32 s7, s7, 0
	s_mul_i32 s48, s69, 0x800000
	s_add_u32 s88, s88, 0x6ab32000
	s_addc_u32 s89, s89, 0
	s_add_u32 s88, s88, s48
	s_addc_u32 s89, s89, 0
	s_lshr_b32 s72, s91, 6
	s_and_b32 s73, s91, 63
	s_lshl_b32 s56, s72, 19
	s_lshl_b32 s57, s73, 7
	s_add_u32 s56, s56, s57
	s_add_u32 s50, s6, s56
	s_addc_u32 s51, s7, 0
	global_load_dwordx4 v[58:61], v44, s[50:51] nt
	global_load_dwordx4 v[62:65], v45, s[50:51] nt
	global_load_dwordx4 v[66:69], v46, s[50:51] nt
	global_load_dwordx4 v[70:73], v47, s[50:51] nt
	global_load_dwordx4 v[74:77], v48, s[50:51] nt
	global_load_dwordx4 v[78:81], v49, s[50:51] nt
	global_load_dwordx4 v[82:85], v50, s[50:51] nt
	global_load_dwordx4 v[86:89], v51, s[50:51] nt
	s_add_u32 s71, s91, s92
	s_cmp_ge_u32 s71, s93
	s_cbranch_scc1 .Ldj0_first0
	s_lshr_b32 s72, s71, 6
	s_and_b32 s73, s71, 63
	s_lshl_b32 s56, s72, 19
	s_lshl_b32 s57, s73, 7
	s_add_u32 s56, s56, s57
	s_add_u32 s50, s6, s56
	s_addc_u32 s51, s7, 0
	global_load_dwordx4 v[90:93], v44, s[50:51] nt
	global_load_dwordx4 v[94:97], v45, s[50:51] nt
	global_load_dwordx4 v[98:101], v46, s[50:51] nt
	global_load_dwordx4 v[102:105], v47, s[50:51] nt
	global_load_dwordx4 v[106:109], v48, s[50:51] nt
	global_load_dwordx4 v[110:113], v49, s[50:51] nt
	global_load_dwordx4 v[114:117], v50, s[50:51] nt
	global_load_dwordx4 v[118:121], v51, s[50:51] nt
	s_waitcnt vmcnt(8)
	s_branch .Ldj0_loop

.Ldj0_loop:
	s_lshr_b32 s72, s91, 6
	s_and_b32 s73, s91, 63
	s_lshl_b32 s58, s73, 17
	s_lshl_b32 s59, s72, 7
	s_add_u32 s58, s58, s59
	ds_write_b32 v52, v58 offset:0
	ds_write_b32 v52, v59 offset:4
	ds_write_b32 v52, v60 offset:8
	ds_write_b32 v52, v61 offset:12
	ds_write_b32 v52, v62 offset:1056
	ds_write_b32 v52, v63 offset:1060
	ds_write_b32 v52, v64 offset:1064
	ds_write_b32 v52, v65 offset:1068
	ds_write_b32 v52, v66 offset:2112
	ds_write_b32 v52, v67 offset:2116
	ds_write_b32 v52, v68 offset:2120
	ds_write_b32 v52, v69 offset:2124
	ds_write_b32 v52, v70 offset:3168
	ds_write_b32 v52, v71 offset:3172
	ds_write_b32 v52, v72 offset:3176
	ds_write_b32 v52, v73 offset:3180
	ds_write_b32 v52, v74 offset:4224
	ds_write_b32 v52, v75 offset:4228
	ds_write_b32 v52, v76 offset:4232
	ds_write_b32 v52, v77 offset:4236
	ds_write_b32 v52, v78 offset:5280
	ds_write_b32 v52, v79 offset:5284
	ds_write_b32 v52, v80 offset:5288
	ds_write_b32 v52, v81 offset:5292
	ds_write_b32 v52, v82 offset:6336
	ds_write_b32 v52, v83 offset:6340
	ds_write_b32 v52, v84 offset:6344
	ds_write_b32 v52, v85 offset:6348
	ds_write_b32 v52, v86 offset:7392
	ds_write_b32 v52, v87 offset:7396
	ds_write_b32 v52, v88 offset:7400
	ds_write_b32 v52, v89 offset:7404
	s_waitcnt lgkmcnt(0)
	s_add_u32 s91, s71, s92
	s_cmp_ge_u32 s91, s93
	s_cbranch_scc1 .Ldj0_nopfa
	s_lshr_b32 s72, s91, 6
	s_and_b32 s73, s91, 63
	s_lshl_b32 s56, s72, 19
	s_lshl_b32 s57, s73, 7
	s_add_u32 s56, s56, s57
	s_add_u32 s50, s6, s56
	s_addc_u32 s51, s7, 0
	global_load_dwordx4 v[58:61], v44, s[50:51] nt
	global_load_dwordx4 v[62:65], v45, s[50:51] nt
	global_load_dwordx4 v[66:69], v46, s[50:51] nt
	global_load_dwordx4 v[70:73], v47, s[50:51] nt
	global_load_dwordx4 v[74:77], v48, s[50:51] nt
	global_load_dwordx4 v[78:81], v49, s[50:51] nt
	global_load_dwordx4 v[82:85], v50, s[50:51] nt
	global_load_dwordx4 v[86:89], v51, s[50:51] nt

.Ldj0_goa:
	s_lshr_b32 s72, s71, 6
	s_and_b32 s73, s71, 63
	s_lshl_b32 s58, s73, 17
	s_lshl_b32 s59, s72, 7
	s_add_u32 s58, s58, s59
	ds_write_b32 v52, v90 offset:0
	ds_write_b32 v52, v91 offset:4
	ds_write_b32 v52, v92 offset:8
	ds_write_b32 v52, v93 offset:12
	ds_write_b32 v52, v94 offset:1056
	ds_write_b32 v52, v95 offset:1060
	ds_write_b32 v52, v96 offset:1064
	ds_write_b32 v52, v97 offset:1068
	ds_write_b32 v52, v98 offset:2112
	ds_write_b32 v52, v99 offset:2116
	ds_write_b32 v52, v100 offset:2120
	ds_write_b32 v52, v101 offset:2124
	ds_write_b32 v52, v102 offset:3168
	ds_write_b32 v52, v103 offset:3172
	ds_write_b32 v52, v104 offset:3176
	ds_write_b32 v52, v105 offset:3180
	ds_write_b32 v52, v106 offset:4224
	ds_write_b32 v52, v107 offset:4228
	ds_write_b32 v52, v108 offset:4232
	ds_write_b32 v52, v109 offset:4236
	ds_write_b32 v52, v110 offset:5280
	ds_write_b32 v52, v111 offset:5284
	ds_write_b32 v52, v112 offset:5288
	ds_write_b32 v52, v113 offset:5292
	ds_write_b32 v52, v114 offset:6336
	ds_write_b32 v52, v115 offset:6340
	ds_write_b32 v52, v116 offset:6344
	ds_write_b32 v52, v117 offset:6348
	ds_write_b32 v52, v118 offset:7392
	ds_write_b32 v52, v119 offset:7396
	ds_write_b32 v52, v120 offset:7400
	ds_write_b32 v52, v121 offset:7404
	s_waitcnt lgkmcnt(0)
	s_add_u32 s71, s91, s92
	s_cmp_ge_u32 s71, s93
	s_cbranch_scc1 .Ldj0_nopfb
	s_lshr_b32 s72, s71, 6
	s_and_b32 s73, s71, 63
	s_lshl_b32 s56, s72, 19
	s_lshl_b32 s57, s73, 7
	s_add_u32 s56, s56, s57
	s_add_u32 s50, s6, s56
	s_addc_u32 s51, s7, 0
	global_load_dwordx4 v[90:93], v44, s[50:51] nt
	global_load_dwordx4 v[94:97], v45, s[50:51] nt
	global_load_dwordx4 v[98:101], v46, s[50:51] nt
	global_load_dwordx4 v[102:105], v47, s[50:51] nt
	global_load_dwordx4 v[106:109], v48, s[50:51] nt
	global_load_dwordx4 v[110:113], v49, s[50:51] nt
	global_load_dwordx4 v[114:117], v50, s[50:51] nt
	global_load_dwordx4 v[118:121], v51, s[50:51] nt

.Ldj9_all:
	v_readfirstlane_b32 s5, v0
	s_lshr_b32 s5, s5, 6
	s_lshl_b32 s2, s2, 3
	s_add_u32 s2, s2, s5
	s_lshl_b32 s92, s4, 3
	v_mbcnt_lo_u32_b32 v41, -1, 0
	v_mbcnt_hi_u32_b32 v41, -1, v41
	v_lshrrev_b32_e32 v42, 3, v41
	v_and_b32_e32 v43, 7, v41
	v_mul_u32_u24_e32 v44, 0x6000, v42
	v_lshl_add_u32 v44, v43, 4, v44
	v_add_u32_e32 v45, 0x30000, v44
	v_add_u32_e32 v46, 0x60000, v44
	v_add_u32_e32 v47, 0x90000, v44
	v_add_u32_e32 v48, 0xc0000, v44
	v_add_u32_e32 v49, 0xf0000, v44
	v_add_u32_e32 v50, 0x120000, v44
	v_add_u32_e32 v51, 0x150000, v44
	s_lshl_b32 s49, s5, 14
	v_mul_u32_u24_e32 v52, 0x84, v42
	v_lshl_add_u32 v52, v43, 4, v52
	v_add_u32_e32 v52, s49, v52
	v_mul_u32_u24_e32 v53, 0x420, v43
	v_lshl_add_u32 v53, v42, 2, v53
	v_add_u32_e32 v53, s49, v53
	v_lshlrev_b32_e32 v54, 12, v42
	v_lshl_add_u32 v54, v43, 4, v54
	v_add_u32_e32 v55, 0x8000, v54
	v_add_u32_e32 v56, 0x10000, v54
	v_add_u32_e32 v57, 0x18000, v54
	v_lshlrev_b32_e32 v204, 2, v42
	s_mov_b32 s83, 0
.Ldj9_disp:
	s_cmp_eq_u32 s83, 0
	s_cbranch_scc0 .Ldj9_nx0
	s_add_u32 s83, s83, 1
	s_cmp_eq_u32 s3, 0
	s_cbranch_scc0 .Ldj9_disp
	s_mov_b32 s69, 0
	s_mov_b32 s91, 0x0
	s_mov_b32 s93, 0x1800
	s_branch .Ldj9_job
.Ldj9_nx0:
	s_cmp_eq_u32 s83, 1
	s_cbranch_scc0 .Ldj9_nx1
	s_add_u32 s83, s83, 1
	s_cmp_eq_u32 s3, 2
	s_cbranch_scc0 .Ldj9_disp
	s_mov_b32 s69, 1
	s_mov_b32 s91, 0x0
	s_mov_b32 s93, 0x1800
	s_branch .Ldj9_job

.Ldj9_job:
	s_add_u32 s91, s91, s2
	s_cmp_ge_u32 s91, s93
	s_cbranch_scc1 .Ldj9_disp
	s_load_dwordx2 s[6:7], s[86:87], 0x70
	s_load_dwordx2 s[88:89], s[86:87], 0xb0
	s_load_dwordx2 s[74:75], s[86:87], 0x28
	s_mul_i32 s48, s69, 0x3000000
	s_waitcnt lgkmcnt(0)
	s_add_u32 s6, s6, s48
	s_addc_u32 s7, s7, 0
	s_mul_i32 s48, s69, 0x1800000
	s_add_u32 s88, s88, 0x6bb32000
	s_addc_u32 s89, s89, 0
	s_add_u32 s88, s88, s48
	s_addc_u32 s89, s89, 0
	s_lshl_b32 s48, s69, 14
	s_add_u32 s48, s48, 0x2000
	s_add_u32 s74, s74, s48
	s_addc_u32 s75, s75, 0
	s_lshr_b32 s57, s91, 6
	s_mul_i32 s57, s57, 0xaaab
	s_lshr_b32 s72, s57, 17
	s_mul_i32 s57, s72, 0xc0
	s_sub_u32 s73, s91, s57
	s_mul_i32 s56, s72, 0x180000
	s_lshl_b32 s57, s73, 7
	s_add_u32 s56, s56, s57
	s_add_u32 s50, s6, s56
	s_addc_u32 s51, s7, 0
	global_load_dwordx4 v[58:61], v44, s[50:51] nt
	global_load_dwordx4 v[62:65], v45, s[50:51] nt
	global_load_dwordx4 v[66:69], v46, s[50:51] nt
	global_load_dwordx4 v[70:73], v47, s[50:51] nt
	global_load_dwordx4 v[74:77], v48, s[50:51] nt
	global_load_dwordx4 v[78:81], v49, s[50:51] nt
	global_load_dwordx4 v[82:85], v50, s[50:51] nt
	global_load_dwordx4 v[86:89], v51, s[50:51] nt
	s_lshl_b32 s56, s72, 8
	s_add_u32 s50, s74, s56
	s_addc_u32 s51, s75, 0
	global_load_dword v230, v204, s[50:51] offset:0
	global_load_dword v231, v204, s[50:51] offset:32
	global_load_dword v232, v204, s[50:51] offset:64
	global_load_dword v233, v204, s[50:51] offset:96
	global_load_dword v234, v204, s[50:51] offset:128
	global_load_dword v235, v204, s[50:51] offset:160
	global_load_dword v236, v204, s[50:51] offset:192
	global_load_dword v237, v204, s[50:51] offset:224
	s_add_u32 s71, s91, s92
	s_cmp_ge_u32 s71, s93
	s_cbranch_scc1 .Ldj9_first0
	s_lshr_b32 s57, s71, 6
	s_mul_i32 s57, s57, 0xaaab
	s_lshr_b32 s72, s57, 17
	s_mul_i32 s57, s72, 0xc0
	s_sub_u32 s73, s71, s57
	s_mul_i32 s56, s72, 0x180000
	s_lshl_b32 s57, s73, 7
	s_add_u32 s56, s56, s57
	s_add_u32 s50, s6, s56
	s_addc_u32 s51, s7, 0
	global_load_dwordx4 v[90:93], v44, s[50:51] nt
	global_load_dwordx4 v[94:97], v45, s[50:51] nt
	global_load_dwordx4 v[98:101], v46, s[50:51] nt
	global_load_dwordx4 v[102:105], v47, s[50:51] nt
	global_load_dwordx4 v[106:109], v48, s[50:51] nt
	global_load_dwordx4 v[110:113], v49, s[50:51] nt
	global_load_dwordx4 v[114:117], v50, s[50:51] nt
	global_load_dwordx4 v[118:121], v51, s[50:51] nt
	s_lshl_b32 s56, s72, 8
	s_add_u32 s50, s74, s56
	s_addc_u32 s51, s75, 0
	global_load_dword v238, v204, s[50:51] offset:0
	global_load_dword v239, v204, s[50:51] offset:32
	global_load_dword v240, v204, s[50:51] offset:64
	global_load_dword v241, v204, s[50:51] offset:96
	global_load_dword v242, v204, s[50:51] offset:128
	global_load_dword v243, v204, s[50:51] offset:160
	global_load_dword v244, v204, s[50:51] offset:192
	global_load_dword v245, v204, s[50:51] offset:224
	s_waitcnt vmcnt(16)
	s_branch .Ldj9_loop

.Ldj9_loop:
	s_lshr_b32 s57, s91, 6
	s_mul_i32 s57, s57, 0xaaab
	s_lshr_b32 s72, s57, 17
	s_mul_i32 s57, s72, 0xc0
	s_sub_u32 s73, s91, s57
	s_lshl_b32 s58, s73, 5
	s_cmp_lt_u32 s58, 0x800
	s_cbranch_scc1 .Ldj9_rma
	s_cmp_ge_u32 s58, 0x1000
	s_cselect_b32 s59, 0x800, 0
	s_cselect_b32 s57, 0x80, 0
	s_add_u32 s59, s59, 0x800
	s_add_u32 s57, s57, 0x800
	s_sub_u32 s58, s58, s59
	s_lshr_b32 s59, s58, 7
	s_and_b32 s58, s58, 0x7f
	s_lshl_b32 s59, s59, 8
	s_add_u32 s58, s58, s59
	s_add_u32 s58, s58, s57
.Ldj9_rma:
	s_lshl_b32 s58, s58, 12
	s_lshl_b32 s59, s72, 7
	s_add_u32 s58, s58, s59
	v_mul_f32_e32 v58, v58, v230
	v_mul_f32_e32 v59, v59, v230
	v_mul_f32_e32 v60, v60, v230
	v_mul_f32_e32 v61, v61, v230
	v_mul_f32_e32 v62, v62, v231
	v_mul_f32_e32 v63, v63, v231
	v_mul_f32_e32 v64, v64, v231
	v_mul_f32_e32 v65, v65, v231
	v_mul_f32_e32 v66, v66, v232
	v_mul_f32_e32 v67, v67, v232
	v_mul_f32_e32 v68, v68, v232
	v_mul_f32_e32 v69, v69, v232
	v_mul_f32_e32 v70, v70, v233
	v_mul_f32_e32 v71, v71, v233
	v_mul_f32_e32 v72, v72, v233
	v_mul_f32_e32 v73, v73, v233
	v_mul_f32_e32 v74, v74, v234
	v_mul_f32_e32 v75, v75, v234
	v_mul_f32_e32 v76, v76, v234
	v_mul_f32_e32 v77, v77, v234
	v_mul_f32_e32 v78, v78, v235
	v_mul_f32_e32 v79, v79, v235
	v_mul_f32_e32 v80, v80, v235
	v_mul_f32_e32 v81, v81, v235
	v_mul_f32_e32 v82, v82, v236
	v_mul_f32_e32 v83, v83, v236
	v_mul_f32_e32 v84, v84, v236
	v_mul_f32_e32 v85, v85, v236
	v_mul_f32_e32 v86, v86, v237
	v_mul_f32_e32 v87, v87, v237
	v_mul_f32_e32 v88, v88, v237
	v_mul_f32_e32 v89, v89, v237
	ds_write_b32 v52, v58 offset:0
	ds_write_b32 v52, v59 offset:4
	ds_write_b32 v52, v60 offset:8
	ds_write_b32 v52, v61 offset:12
	ds_write_b32 v52, v62 offset:1056
	ds_write_b32 v52, v63 offset:1060
	ds_write_b32 v52, v64 offset:1064
	ds_write_b32 v52, v65 offset:1068
	ds_write_b32 v52, v66 offset:2112
	ds_write_b32 v52, v67 offset:2116
	ds_write_b32 v52, v68 offset:2120
	ds_write_b32 v52, v69 offset:2124
	ds_write_b32 v52, v70 offset:3168
	ds_write_b32 v52, v71 offset:3172
	ds_write_b32 v52, v72 offset:3176
	ds_write_b32 v52, v73 offset:3180
	ds_write_b32 v52, v74 offset:4224
	ds_write_b32 v52, v75 offset:4228
	ds_write_b32 v52, v76 offset:4232
	ds_write_b32 v52, v77 offset:4236
	ds_write_b32 v52, v78 offset:5280
	ds_write_b32 v52, v79 offset:5284
	ds_write_b32 v52, v80 offset:5288
	ds_write_b32 v52, v81 offset:5292
	ds_write_b32 v52, v82 offset:6336
	ds_write_b32 v52, v83 offset:6340
	ds_write_b32 v52, v84 offset:6344
	ds_write_b32 v52, v85 offset:6348
	ds_write_b32 v52, v86 offset:7392
	ds_write_b32 v52, v87 offset:7396
	ds_write_b32 v52, v88 offset:7400
	ds_write_b32 v52, v89 offset:7404
	s_waitcnt lgkmcnt(0)
	s_add_u32 s91, s71, s92
	s_cmp_ge_u32 s91, s93
	s_cbranch_scc1 .Ldj9_nopfa
	s_lshr_b32 s57, s91, 6
	s_mul_i32 s57, s57, 0xaaab
	s_lshr_b32 s72, s57, 17
	s_mul_i32 s57, s72, 0xc0
	s_sub_u32 s73, s91, s57
	s_mul_i32 s56, s72, 0x180000
	s_lshl_b32 s57, s73, 7
	s_add_u32 s56, s56, s57
	s_add_u32 s50, s6, s56
	s_addc_u32 s51, s7, 0
	global_load_dwordx4 v[58:61], v44, s[50:51] nt
	global_load_dwordx4 v[62:65], v45, s[50:51] nt
	global_load_dwordx4 v[66:69], v46, s[50:51] nt
	global_load_dwordx4 v[70:73], v47, s[50:51] nt
	global_load_dwordx4 v[74:77], v48, s[50:51] nt
	global_load_dwordx4 v[78:81], v49, s[50:51] nt
	global_load_dwordx4 v[82:85], v50, s[50:51] nt
	global_load_dwordx4 v[86:89], v51, s[50:51] nt
	s_lshl_b32 s56, s72, 8
	s_add_u32 s50, s74, s56
	s_addc_u32 s51, s75, 0
	global_load_dword v230, v204, s[50:51] offset:0
	global_load_dword v231, v204, s[50:51] offset:32
	global_load_dword v232, v204, s[50:51] offset:64
	global_load_dword v233, v204, s[50:51] offset:96
	global_load_dword v234, v204, s[50:51] offset:128
	global_load_dword v235, v204, s[50:51] offset:160
	global_load_dword v236, v204, s[50:51] offset:192
	global_load_dword v237, v204, s[50:51] offset:224

.Ldj9_goa:
	s_lshr_b32 s57, s71, 6
	s_mul_i32 s57, s57, 0xaaab
	s_lshr_b32 s72, s57, 17
	s_mul_i32 s57, s72, 0xc0
	s_sub_u32 s73, s71, s57
	s_lshl_b32 s58, s73, 5
	s_cmp_lt_u32 s58, 0x800
	s_cbranch_scc1 .Ldj9_rmb
	s_cmp_ge_u32 s58, 0x1000
	s_cselect_b32 s59, 0x800, 0
	s_cselect_b32 s57, 0x80, 0
	s_add_u32 s59, s59, 0x800
	s_add_u32 s57, s57, 0x800
	s_sub_u32 s58, s58, s59
	s_lshr_b32 s59, s58, 7
	s_and_b32 s58, s58, 0x7f
	s_lshl_b32 s59, s59, 8
	s_add_u32 s58, s58, s59
	s_add_u32 s58, s58, s57
.Ldj9_rmb:
	s_lshl_b32 s58, s58, 12
	s_lshl_b32 s59, s72, 7
	s_add_u32 s58, s58, s59
	v_mul_f32_e32 v90, v90, v238
	v_mul_f32_e32 v91, v91, v238
	v_mul_f32_e32 v92, v92, v238
	v_mul_f32_e32 v93, v93, v238
	v_mul_f32_e32 v94, v94, v239
	v_mul_f32_e32 v95, v95, v239
	v_mul_f32_e32 v96, v96, v239
	v_mul_f32_e32 v97, v97, v239
	v_mul_f32_e32 v98, v98, v240
	v_mul_f32_e32 v99, v99, v240
	v_mul_f32_e32 v100, v100, v240
	v_mul_f32_e32 v101, v101, v240
	v_mul_f32_e32 v102, v102, v241
	v_mul_f32_e32 v103, v103, v241
	v_mul_f32_e32 v104, v104, v241
	v_mul_f32_e32 v105, v105, v241
	v_mul_f32_e32 v106, v106, v242
	v_mul_f32_e32 v107, v107, v242
	v_mul_f32_e32 v108, v108, v242
	v_mul_f32_e32 v109, v109, v242
	v_mul_f32_e32 v110, v110, v243
	v_mul_f32_e32 v111, v111, v243
	v_mul_f32_e32 v112, v112, v243
	v_mul_f32_e32 v113, v113, v243
	v_mul_f32_e32 v114, v114, v244
	v_mul_f32_e32 v115, v115, v244
	v_mul_f32_e32 v116, v116, v244
	v_mul_f32_e32 v117, v117, v244
	v_mul_f32_e32 v118, v118, v245
	v_mul_f32_e32 v119, v119, v245
	v_mul_f32_e32 v120, v120, v245
	v_mul_f32_e32 v121, v121, v245
	ds_write_b32 v52, v90 offset:0
	ds_write_b32 v52, v91 offset:4
	ds_write_b32 v52, v92 offset:8
	ds_write_b32 v52, v93 offset:12
	ds_write_b32 v52, v94 offset:1056
	ds_write_b32 v52, v95 offset:1060
	ds_write_b32 v52, v96 offset:1064
	ds_write_b32 v52, v97 offset:1068
	ds_write_b32 v52, v98 offset:2112
	ds_write_b32 v52, v99 offset:2116
	ds_write_b32 v52, v100 offset:2120
	ds_write_b32 v52, v101 offset:2124
	ds_write_b32 v52, v102 offset:3168
	ds_write_b32 v52, v103 offset:3172
	ds_write_b32 v52, v104 offset:3176
	ds_write_b32 v52, v105 offset:3180
	ds_write_b32 v52, v106 offset:4224
	ds_write_b32 v52, v107 offset:4228
	ds_write_b32 v52, v108 offset:4232
	ds_write_b32 v52, v109 offset:4236
	ds_write_b32 v52, v110 offset:5280
	ds_write_b32 v52, v111 offset:5284
	ds_write_b32 v52, v112 offset:5288
	ds_write_b32 v52, v113 offset:5292
	ds_write_b32 v52, v114 offset:6336
	ds_write_b32 v52, v115 offset:6340
	ds_write_b32 v52, v116 offset:6344
	ds_write_b32 v52, v117 offset:6348
	ds_write_b32 v52, v118 offset:7392
	ds_write_b32 v52, v119 offset:7396
	ds_write_b32 v52, v120 offset:7400
	ds_write_b32 v52, v121 offset:7404
	s_waitcnt lgkmcnt(0)
	s_add_u32 s71, s91, s92
	s_cmp_ge_u32 s71, s93
	s_cbranch_scc1 .Ldj9_nopfb
	s_lshr_b32 s57, s71, 6
	s_mul_i32 s57, s57, 0xaaab
	s_lshr_b32 s72, s57, 17
	s_mul_i32 s57, s72, 0xc0
	s_sub_u32 s73, s71, s57
	s_mul_i32 s56, s72, 0x180000
	s_lshl_b32 s57, s73, 7
	s_add_u32 s56, s56, s57
	s_add_u32 s50, s6, s56
	s_addc_u32 s51, s7, 0
	global_load_dwordx4 v[90:93], v44, s[50:51] nt
	global_load_dwordx4 v[94:97], v45, s[50:51] nt
	global_load_dwordx4 v[98:101], v46, s[50:51] nt
	global_load_dwordx4 v[102:105], v47, s[50:51] nt
	global_load_dwordx4 v[106:109], v48, s[50:51] nt
	global_load_dwordx4 v[110:113], v49, s[50:51] nt
	global_load_dwordx4 v[114:117], v50, s[50:51] nt
	global_load_dwordx4 v[118:121], v51, s[50:51] nt
	s_lshl_b32 s56, s72, 8
	s_add_u32 s50, s74, s56
	s_addc_u32 s51, s75, 0
	global_load_dword v238, v204, s[50:51] offset:0
	global_load_dword v239, v204, s[50:51] offset:32
	global_load_dword v240, v204, s[50:51] offset:64
	global_load_dword v241, v204, s[50:51] offset:96
	global_load_dword v242, v204, s[50:51] offset:128
	global_load_dword v243, v204, s[50:51] offset:160
	global_load_dword v244, v204, s[50:51] offset:192
	global_load_dword v245, v204, s[50:51] offset:224
